# final RMSNorm fused into layer-1 out-projection epilogue (row partial sums exchanged inside the XCD; out->final barrier XCD-local; unnormalised stream never written/re-read)
# speedup vs baseline: 1.0242x; 1.0242x over previous
.LBB0_766:
	s_add_u32 s10, s8, 0xfffc0080
	s_addc_u32 s11, s9, -1
	s_add_i32 s38, 0, 0x10000
	v_add_u32_e32 v146, s38, v151
	ds_read_b128 v[120:123], v146
	ds_read_b128 v[124:127], v146 offset:1024
	ds_read_b128 v[142:145], v146 offset:2048
	ds_read_b128 v[146:149], v146 offset:3072
	s_cmp_eq_u32 s37, 12
	s_cselect_b32 s13, s1, s11
	s_cselect_b32 s12, s0, s10
	s_cselect_b32 s11, s7, s36
	s_cselect_b32 s10, s6, s35
	v_lshl_add_u64 v[186:187], s[8:9], 0, v[138:139]
	s_add_i32 m0, s20, 0xc000
	ds_read_b128 v[154:157], v153
	ds_read_b128 v[158:161], v153 offset:1024
	ds_read_b128 v[162:165], v153 offset:2048
	ds_read_b128 v[166:169], v153 offset:3072
	ds_read_b128 v[170:173], v153 offset:4096
	ds_read_b128 v[174:177], v153 offset:5120
	ds_read_b128 v[178:181], v153 offset:6144
	ds_read_b128 v[182:185], v153 offset:7168
	global_load_lds_dwordx4 v[186:187], off
	v_lshl_add_u64 v[186:187], s[8:9], 0, v[140:141]
	s_add_i32 m0, s20, 0xe000
	s_nop 0
	global_load_lds_dwordx4 v[186:187], off
	s_waitcnt lgkmcnt(8)
	s_barrier
	s_waitcnt lgkmcnt(0)
	s_setprio 1
	s_waitcnt lgkmcnt(0)
	v_mfma_f32_16x16x32_bf16 v[132:135], v[120:123], v[154:157], v[132:135]
	v_mfma_f32_16x16x32_bf16 v[128:131], v[142:145], v[154:157], v[128:131]
	v_mfma_f32_16x16x32_bf16 v[116:119], v[120:123], v[162:165], v[116:119]
	v_mfma_f32_16x16x32_bf16 v[112:115], v[142:145], v[162:165], v[112:115]
	v_mfma_f32_16x16x32_bf16 v[108:111], v[120:123], v[170:173], v[108:111]
	v_mfma_f32_16x16x32_bf16 v[104:107], v[142:145], v[170:173], v[104:107]
	v_mfma_f32_16x16x32_bf16 v[100:103], v[120:123], v[178:181], v[100:103]
	v_mfma_f32_16x16x32_bf16 v[96:99], v[142:145], v[178:181], v[96:99]
	v_mfma_f32_16x16x32_bf16 v[132:135], v[124:127], v[158:161], v[132:135]
	v_mfma_f32_16x16x32_bf16 v[128:131], v[146:149], v[158:161], v[128:131]
	v_mfma_f32_16x16x32_bf16 v[116:119], v[124:127], v[166:169], v[116:119]
	v_mfma_f32_16x16x32_bf16 v[112:115], v[146:149], v[166:169], v[112:115]
	v_mfma_f32_16x16x32_bf16 v[108:111], v[124:127], v[174:177], v[108:111]
	v_mfma_f32_16x16x32_bf16 v[104:107], v[146:149], v[174:177], v[104:107]
	v_mfma_f32_16x16x32_bf16 v[100:103], v[124:127], v[182:185], v[100:103]
	v_mfma_f32_16x16x32_bf16 v[96:99], v[146:149], v[182:185], v[96:99]
	s_setprio 0
	s_barrier
	s_add_i32 s40, 0, 0x14000
	s_add_i32 s38, s38, s19
	v_add_u32_e32 v208, s40, v151
	v_lshl_add_u64 v[212:213], s[10:11], 0, v[194:195]
	s_mov_b32 m0, s38
	ds_read_b128 v[186:189], v208
	ds_read_b128 v[190:193], v208 offset:1024
	ds_read_b128 v[204:207], v208 offset:2048
	ds_read_b128 v[208:211], v208 offset:3072
	global_load_lds_dwordx4 v[212:213], off
	v_lshl_add_u64 v[214:215], s[10:11], 0, v[136:137]
	s_add_i32 m0, s38, 0x2000
	s_nop 0
	global_load_lds_dwordx4 v[214:215], off
	s_barrier
	s_waitcnt lgkmcnt(0)
	s_setprio 1
	s_waitcnt lgkmcnt(0)
	v_mfma_f32_16x16x32_bf16 v[64:67], v[186:189], v[154:157], v[64:67]
	v_mfma_f32_16x16x32_bf16 v[56:59], v[204:207], v[154:157], v[56:59]
	v_mfma_f32_16x16x32_bf16 v[52:55], v[186:189], v[162:165], v[52:55]
	v_mfma_f32_16x16x32_bf16 v[48:51], v[204:207], v[162:165], v[48:51]
	v_mfma_f32_16x16x32_bf16 v[44:47], v[186:189], v[170:173], v[44:47]
	v_mfma_f32_16x16x32_bf16 v[40:43], v[204:207], v[170:173], v[40:43]
	v_mfma_f32_16x16x32_bf16 v[36:39], v[186:189], v[178:181], v[36:39]
	v_mfma_f32_16x16x32_bf16 v[32:35], v[204:207], v[178:181], v[32:35]
	v_mfma_f32_16x16x32_bf16 v[64:67], v[190:193], v[158:161], v[64:67]
	v_mfma_f32_16x16x32_bf16 v[56:59], v[208:211], v[158:161], v[56:59]
	v_mfma_f32_16x16x32_bf16 v[52:55], v[190:193], v[166:169], v[52:55]
	v_mfma_f32_16x16x32_bf16 v[48:51], v[208:211], v[166:169], v[48:51]
	v_mfma_f32_16x16x32_bf16 v[44:47], v[190:193], v[174:177], v[44:47]
	v_mfma_f32_16x16x32_bf16 v[40:43], v[208:211], v[174:177], v[40:43]
	v_mfma_f32_16x16x32_bf16 v[36:39], v[190:193], v[182:185], v[36:39]
	v_mfma_f32_16x16x32_bf16 v[32:35], v[208:211], v[182:185], v[32:35]
	s_setprio 0
	s_mov_b32 m0, s20
	v_lshl_add_u64 v[216:217], s[12:13], 0, v[194:195]
	s_barrier
	ds_read_b128 v[154:157], v153 offset:16384
	ds_read_b128 v[158:161], v153 offset:17408
	ds_read_b128 v[162:165], v153 offset:18432
	ds_read_b128 v[166:169], v153 offset:19456
	ds_read_b128 v[170:173], v153 offset:20480
	ds_read_b128 v[174:177], v153 offset:21504
	ds_read_b128 v[178:181], v153 offset:22528
	ds_read_b128 v[182:185], v153 offset:23552
	global_load_lds_dwordx4 v[216:217], off
	v_lshl_add_u64 v[236:237], s[12:13], 0, v[136:137]
	s_mov_b32 m0, s21
	s_nop 0
	global_load_lds_dwordx4 v[236:237], off
	s_barrier
	s_waitcnt lgkmcnt(0)
	s_setprio 1
	s_waitcnt lgkmcnt(0)
	v_mfma_f32_16x16x32_bf16 v[92:95], v[120:123], v[154:157], v[92:95]
	v_mfma_f32_16x16x32_bf16 v[88:91], v[142:145], v[154:157], v[88:91]
	v_mfma_f32_16x16x32_bf16 v[84:87], v[120:123], v[162:165], v[84:87]
	v_mfma_f32_16x16x32_bf16 v[80:83], v[142:145], v[162:165], v[80:83]
	v_mfma_f32_16x16x32_bf16 v[76:79], v[120:123], v[170:173], v[76:79]
	v_mfma_f32_16x16x32_bf16 v[72:75], v[142:145], v[170:173], v[72:75]
	v_mfma_f32_16x16x32_bf16 v[68:71], v[120:123], v[178:181], v[68:71]
	v_mfma_f32_16x16x32_bf16 v[60:63], v[142:145], v[178:181], v[60:63]
	v_mfma_f32_16x16x32_bf16 v[92:95], v[124:127], v[158:161], v[92:95]
	v_mfma_f32_16x16x32_bf16 v[88:91], v[146:149], v[158:161], v[88:91]
	v_mfma_f32_16x16x32_bf16 v[84:87], v[124:127], v[166:169], v[84:87]
	v_mfma_f32_16x16x32_bf16 v[80:83], v[146:149], v[166:169], v[80:83]
	v_mfma_f32_16x16x32_bf16 v[76:79], v[124:127], v[174:177], v[76:79]
	v_mfma_f32_16x16x32_bf16 v[72:75], v[146:149], v[174:177], v[72:75]
	v_mfma_f32_16x16x32_bf16 v[68:71], v[124:127], v[182:185], v[68:71]
	v_mfma_f32_16x16x32_bf16 v[60:63], v[146:149], v[182:185], v[60:63]
	s_setprio 0
	s_barrier
	s_add_u32 s38, s10, 0x40000
	s_addc_u32 s39, s11, 0
	s_add_i32 s40, s40, s19
	v_lshl_add_u64 v[120:121], s[38:39], 0, v[194:195]
	s_mov_b32 m0, s40
	s_nop 0
	global_load_lds_dwordx4 v[120:121], off
	v_lshl_add_u64 v[120:121], s[38:39], 0, v[136:137]
	s_add_i32 m0, s40, 0x2000
	s_nop 0
	global_load_lds_dwordx4 v[120:121], off
	s_waitcnt vmcnt(6)
	s_barrier
	s_setprio 1
	v_mfma_f32_16x16x32_bf16 v[28:31], v[186:189], v[154:157], v[28:31]
	v_mfma_f32_16x16x32_bf16 v[24:27], v[204:207], v[154:157], v[24:27]
	v_mfma_f32_16x16x32_bf16 v[20:23], v[186:189], v[162:165], v[20:23]
	v_mfma_f32_16x16x32_bf16 v[16:19], v[204:207], v[162:165], v[16:19]
	v_mfma_f32_16x16x32_bf16 v[12:15], v[186:189], v[170:173], v[12:15]
	v_mfma_f32_16x16x32_bf16 v[8:11], v[204:207], v[170:173], v[8:11]
	v_mfma_f32_16x16x32_bf16 v[4:7], v[186:189], v[178:181], v[4:7]
	v_mfma_f32_16x16x32_bf16 v[0:3], v[204:207], v[178:181], v[0:3]
	v_mfma_f32_16x16x32_bf16 v[28:31], v[190:193], v[158:161], v[28:31]
	v_mfma_f32_16x16x32_bf16 v[24:27], v[208:211], v[158:161], v[24:27]
	v_mfma_f32_16x16x32_bf16 v[20:23], v[190:193], v[166:169], v[20:23]
	v_mfma_f32_16x16x32_bf16 v[16:19], v[208:211], v[166:169], v[16:19]
	v_mfma_f32_16x16x32_bf16 v[12:15], v[190:193], v[174:177], v[12:15]
	v_mfma_f32_16x16x32_bf16 v[8:11], v[208:211], v[174:177], v[8:11]
	v_mfma_f32_16x16x32_bf16 v[4:7], v[190:193], v[182:185], v[4:7]
	v_mfma_f32_16x16x32_bf16 v[0:3], v[208:211], v[182:185], v[0:3]
	s_setprio 0
	s_add_i32 s38, 0, 0x18000
	v_add_u32_e32 v146, s38, v151
	s_barrier
	ds_read_b128 v[120:123], v146
	ds_read_b128 v[124:127], v146 offset:1024
	ds_read_b128 v[142:145], v146 offset:2048
	ds_read_b128 v[146:149], v146 offset:3072
	s_add_u32 s12, s12, 0x40000
	s_addc_u32 s13, s13, 0
	s_mov_b32 m0, s22
	v_lshl_add_u64 v[186:187], s[12:13], 0, v[194:195]
	ds_read_b128 v[154:157], v153 offset:32768
	ds_read_b128 v[158:161], v153 offset:33792
	ds_read_b128 v[162:165], v153 offset:34816
	ds_read_b128 v[166:169], v153 offset:35840
	ds_read_b128 v[170:173], v153 offset:36864
	ds_read_b128 v[174:177], v153 offset:37888
	ds_read_b128 v[178:181], v153 offset:38912
	ds_read_b128 v[182:185], v153 offset:39936
	global_load_lds_dwordx4 v[186:187], off
	v_lshl_add_u64 v[186:187], s[12:13], 0, v[136:137]
	s_mov_b32 m0, s23
	s_nop 0
	global_load_lds_dwordx4 v[186:187], off
	s_waitcnt lgkmcnt(8)
	s_barrier
	s_waitcnt lgkmcnt(0)
	s_setprio 1
	s_waitcnt lgkmcnt(0)
	v_mfma_f32_16x16x32_bf16 v[132:135], v[120:123], v[154:157], v[132:135]
	v_mfma_f32_16x16x32_bf16 v[128:131], v[142:145], v[154:157], v[128:131]
	v_mfma_f32_16x16x32_bf16 v[116:119], v[120:123], v[162:165], v[116:119]
	v_mfma_f32_16x16x32_bf16 v[112:115], v[142:145], v[162:165], v[112:115]
	v_mfma_f32_16x16x32_bf16 v[108:111], v[120:123], v[170:173], v[108:111]
	v_mfma_f32_16x16x32_bf16 v[104:107], v[142:145], v[170:173], v[104:107]
	v_mfma_f32_16x16x32_bf16 v[100:103], v[120:123], v[178:181], v[100:103]
	v_mfma_f32_16x16x32_bf16 v[96:99], v[142:145], v[178:181], v[96:99]
	v_mfma_f32_16x16x32_bf16 v[132:135], v[124:127], v[158:161], v[132:135]
	v_mfma_f32_16x16x32_bf16 v[128:131], v[146:149], v[158:161], v[128:131]
	v_mfma_f32_16x16x32_bf16 v[116:119], v[124:127], v[166:169], v[116:119]
	v_mfma_f32_16x16x32_bf16 v[112:115], v[146:149], v[166:169], v[112:115]
	v_mfma_f32_16x16x32_bf16 v[108:111], v[124:127], v[174:177], v[108:111]
	v_mfma_f32_16x16x32_bf16 v[104:107], v[146:149], v[174:177], v[104:107]
	v_mfma_f32_16x16x32_bf16 v[100:103], v[124:127], v[182:185], v[100:103]
	v_mfma_f32_16x16x32_bf16 v[96:99], v[146:149], v[182:185], v[96:99]
	s_setprio 0
	s_barrier
	s_add_i32 s12, 0, 0x1c000
	s_add_i32 s13, s38, s19
	v_add_u32_e32 v208, s12, v151
	v_lshl_add_u64 v[212:213], v[212:213], 0, s[82:83]
	s_mov_b32 m0, s13
	ds_read_b128 v[186:189], v208
	ds_read_b128 v[190:193], v208 offset:1024
	ds_read_b128 v[204:207], v208 offset:2048
	ds_read_b128 v[208:211], v208 offset:3072
	global_load_lds_dwordx4 v[212:213], off
	v_lshl_add_u64 v[212:213], v[214:215], 0, s[82:83]
	s_add_i32 m0, s13, 0x2000
	s_nop 0
	global_load_lds_dwordx4 v[212:213], off
	s_barrier
	s_waitcnt lgkmcnt(0)
	s_setprio 1
	s_waitcnt lgkmcnt(0)
	v_mfma_f32_16x16x32_bf16 v[64:67], v[186:189], v[154:157], v[64:67]
	v_mfma_f32_16x16x32_bf16 v[56:59], v[204:207], v[154:157], v[56:59]
	v_mfma_f32_16x16x32_bf16 v[52:55], v[186:189], v[162:165], v[52:55]
	v_mfma_f32_16x16x32_bf16 v[48:51], v[204:207], v[162:165], v[48:51]
	v_mfma_f32_16x16x32_bf16 v[44:47], v[186:189], v[170:173], v[44:47]
	v_mfma_f32_16x16x32_bf16 v[40:43], v[204:207], v[170:173], v[40:43]
	v_mfma_f32_16x16x32_bf16 v[36:39], v[186:189], v[178:181], v[36:39]
	v_mfma_f32_16x16x32_bf16 v[32:35], v[204:207], v[178:181], v[32:35]
	v_mfma_f32_16x16x32_bf16 v[64:67], v[190:193], v[158:161], v[64:67]
	v_mfma_f32_16x16x32_bf16 v[56:59], v[208:211], v[158:161], v[56:59]
	v_mfma_f32_16x16x32_bf16 v[52:55], v[190:193], v[166:169], v[52:55]
	v_mfma_f32_16x16x32_bf16 v[48:51], v[208:211], v[166:169], v[48:51]
	v_mfma_f32_16x16x32_bf16 v[44:47], v[190:193], v[174:177], v[44:47]
	v_mfma_f32_16x16x32_bf16 v[40:43], v[208:211], v[174:177], v[40:43]
	v_mfma_f32_16x16x32_bf16 v[36:39], v[190:193], v[182:185], v[36:39]
	v_mfma_f32_16x16x32_bf16 v[32:35], v[208:211], v[182:185], v[32:35]
	s_setprio 0
	s_mov_b32 m0, s26
	v_lshl_add_u64 v[212:213], v[216:217], 0, s[82:83]
	s_barrier
	ds_read_b128 v[154:157], v153 offset:49152
	ds_read_b128 v[158:161], v153 offset:50176
	ds_read_b128 v[162:165], v153 offset:51200
	ds_read_b128 v[166:169], v153 offset:52224
	ds_read_b128 v[170:173], v153 offset:53248
	ds_read_b128 v[174:177], v153 offset:54272
	ds_read_b128 v[178:181], v153 offset:55296
	ds_read_b128 v[182:185], v153 offset:56320
	global_load_lds_dwordx4 v[212:213], off
	v_lshl_add_u64 v[212:213], v[236:237], 0, s[82:83]
	s_mov_b32 m0, s27
	s_nop 0
	global_load_lds_dwordx4 v[212:213], off
	s_barrier
	s_waitcnt lgkmcnt(0)
	s_setprio 1
	s_waitcnt lgkmcnt(0)
	v_mfma_f32_16x16x32_bf16 v[92:95], v[120:123], v[154:157], v[92:95]
	v_mfma_f32_16x16x32_bf16 v[88:91], v[142:145], v[154:157], v[88:91]
	v_mfma_f32_16x16x32_bf16 v[84:87], v[120:123], v[162:165], v[84:87]
	v_mfma_f32_16x16x32_bf16 v[80:83], v[142:145], v[162:165], v[80:83]
	v_mfma_f32_16x16x32_bf16 v[76:79], v[120:123], v[170:173], v[76:79]
	v_mfma_f32_16x16x32_bf16 v[72:75], v[142:145], v[170:173], v[72:75]
	v_mfma_f32_16x16x32_bf16 v[68:71], v[120:123], v[178:181], v[68:71]
	v_mfma_f32_16x16x32_bf16 v[60:63], v[142:145], v[178:181], v[60:63]
	v_mfma_f32_16x16x32_bf16 v[92:95], v[124:127], v[158:161], v[92:95]
	v_mfma_f32_16x16x32_bf16 v[88:91], v[146:149], v[158:161], v[88:91]
	v_mfma_f32_16x16x32_bf16 v[84:87], v[124:127], v[166:169], v[84:87]
	v_mfma_f32_16x16x32_bf16 v[80:83], v[146:149], v[166:169], v[80:83]
	v_mfma_f32_16x16x32_bf16 v[76:79], v[124:127], v[174:177], v[76:79]
	v_mfma_f32_16x16x32_bf16 v[72:75], v[146:149], v[174:177], v[72:75]
	v_mfma_f32_16x16x32_bf16 v[68:71], v[124:127], v[182:185], v[68:71]
	v_mfma_f32_16x16x32_bf16 v[60:63], v[146:149], v[182:185], v[60:63]
	s_setprio 0
	s_barrier
	s_add_u32 s10, s10, 0x40080
	s_addc_u32 s11, s11, 0
	s_add_i32 s12, s12, s19
	v_lshl_add_u64 v[120:121], s[10:11], 0, v[194:195]
	s_mov_b32 m0, s12
	s_nop 0
	global_load_lds_dwordx4 v[120:121], off
	v_lshl_add_u64 v[120:121], s[10:11], 0, v[136:137]
	s_add_i32 m0, s12, 0x2000
	s_nop 0
	global_load_lds_dwordx4 v[120:121], off
	s_waitcnt vmcnt(6)
	s_barrier
	s_setprio 1
	v_mfma_f32_16x16x32_bf16 v[28:31], v[186:189], v[154:157], v[28:31]
	v_mfma_f32_16x16x32_bf16 v[24:27], v[204:207], v[154:157], v[24:27]
	v_mfma_f32_16x16x32_bf16 v[20:23], v[186:189], v[162:165], v[20:23]
	v_mfma_f32_16x16x32_bf16 v[16:19], v[204:207], v[162:165], v[16:19]
	v_mfma_f32_16x16x32_bf16 v[12:15], v[186:189], v[170:173], v[12:15]
	v_mfma_f32_16x16x32_bf16 v[8:11], v[204:207], v[170:173], v[8:11]
	v_mfma_f32_16x16x32_bf16 v[4:7], v[186:189], v[178:181], v[4:7]
	v_mfma_f32_16x16x32_bf16 v[0:3], v[204:207], v[178:181], v[0:3]
	v_mfma_f32_16x16x32_bf16 v[28:31], v[190:193], v[158:161], v[28:31]
	v_mfma_f32_16x16x32_bf16 v[24:27], v[208:211], v[158:161], v[24:27]
	v_mfma_f32_16x16x32_bf16 v[20:23], v[190:193], v[166:169], v[20:23]
	v_mfma_f32_16x16x32_bf16 v[16:19], v[208:211], v[166:169], v[16:19]
	v_mfma_f32_16x16x32_bf16 v[12:15], v[190:193], v[174:177], v[12:15]
	v_mfma_f32_16x16x32_bf16 v[8:11], v[208:211], v[174:177], v[8:11]
	v_mfma_f32_16x16x32_bf16 v[4:7], v[190:193], v[182:185], v[4:7]
	v_mfma_f32_16x16x32_bf16 v[0:3], v[208:211], v[182:185], v[0:3]
	s_setprio 0
	s_add_i32 s37, s37, 2
	s_add_u32 s8, s8, 0x100
	s_addc_u32 s9, s9, 0
	s_add_u32 s35, s35, 0x100
	s_addc_u32 s36, s36, 0
	s_cmp_gt_u32 s37, 13
	s_barrier
	s_cbranch_scc0 .LBB0_766
	s_lshr_b32 s8, s31, 4
	s_mulk_i32 s8, 0xc00
	s_ashr_i32 s9, s8, 31
	v_lshl_or_b32 v120, s34, 8, v152
	s_lshl_b64 s[8:9], s[8:9], 2
	s_add_u32 s8, s24, s8
	v_ashrrev_i32_e32 v121, 31, v120
	v_lshl_add_u32 v148, s31, 8, v150
	s_addc_u32 s9, s25, s9
	v_lshlrev_b64 v[146:147], 2, v[120:121]
	v_lshl_add_u64 v[142:143], s[8:9], 0, v[146:147]
	v_ashrrev_i32_e32 v149, 31, v148
	v_readlane_b32 s8, v252, 25
	v_lshlrev_b64 v[162:163], 12, v[148:149]
	v_readlane_b32 s9, v252, 26
	v_readlane_b32 s42, v252, 23
	s_nop 3
	s_cmp_lg_u32 s42, 0
	s_cbranch_scc1 .Lfz_normal
	s_cmpk_gt_u32 s14, 0xff
	s_cbranch_scc1 .Lfz_al
	s_barrier
.Lfz_al:
	s_mov_b32 s42, s31
	s_mov_b32 s43, s34
	global_load_dwordx4 v[120:123], v[142:143], off offset:16
	global_load_dwordx4 v[124:127], v[142:143], off
	global_load_dwordx4 v[236:239], v[142:143], off offset:528
	global_load_dwordx4 v[240:243], v[142:143], off offset:512
	s_nop 3
	v_lshl_add_u64 v[144:145], s[8:9], 0, v[162:163]
	v_lshl_add_u64 v[144:145], v[144:145], 0, v[146:147]
	s_mov_b64 s[44:45], 0x10000
	v_lshl_add_u64 v[244:245], v[144:145], 0, s[44:45]
	s_mov_b64 s[44:45], 0x20000
	v_lshl_add_u64 v[246:247], v[144:145], 0, s[44:45]
	s_mov_b64 s[44:45], 0x30000
	v_lshl_add_u64 v[248:249], v[144:145], 0, s[44:45]
	s_mov_b64 s[44:45], 0x80000
	v_lshl_add_u64 v[250:251], v[144:145], 0, s[44:45]
	s_mov_b64 s[44:45], 0x90000
	v_lshl_add_u64 v[216:217], v[144:145], 0, s[44:45]
	s_mov_b64 s[44:45], 0xa0000
	v_lshl_add_u64 v[192:193], v[144:145], 0, s[44:45]
	s_mov_b64 s[44:45], 0xb0000
	v_lshl_add_u64 v[188:189], v[144:145], 0, s[44:45]
	global_load_dwordx4 v[154:157], v[144:145], off offset:16
	global_load_dwordx4 v[158:161], v[144:145], off offset:0
	global_load_dwordx4 v[164:167], v[244:245], off offset:16
	global_load_dwordx4 v[168:171], v[244:245], off offset:0
	global_load_dwordx4 v[172:175], v[246:247], off offset:16
	global_load_dwordx4 v[176:179], v[246:247], off offset:0
	global_load_dwordx4 v[180:183], v[248:249], off offset:16
	global_load_dwordx4 v[184:187], v[248:249], off offset:0
	global_load_dwordx4 v[204:207], v[250:251], off offset:16
	global_load_dwordx4 v[208:211], v[250:251], off offset:0
	s_waitcnt vmcnt(8)
	v_pk_fma_f32 v[128:129], v[128:129], v[120:121], v[154:155]
	v_pk_fma_f32 v[130:131], v[130:131], v[122:123], v[156:157]
	v_pk_fma_f32 v[132:133], v[132:133], v[124:125], v[158:159]
	v_pk_fma_f32 v[134:135], v[134:135], v[126:127], v[160:161]
	global_load_dwordx4 v[154:157], v[216:217], off offset:16
	global_load_dwordx4 v[158:161], v[216:217], off offset:0
	s_waitcnt vmcnt(8)
	v_pk_fma_f32 v[112:113], v[112:113], v[120:121], v[164:165]
	v_pk_fma_f32 v[114:115], v[114:115], v[122:123], v[166:167]
	v_pk_fma_f32 v[116:117], v[116:117], v[124:125], v[168:169]
	v_pk_fma_f32 v[118:119], v[118:119], v[126:127], v[170:171]
	global_load_dwordx4 v[164:167], v[192:193], off offset:16
	global_load_dwordx4 v[168:171], v[192:193], off offset:0
	s_waitcnt vmcnt(8)
	v_pk_fma_f32 v[104:105], v[104:105], v[120:121], v[172:173]
	v_pk_fma_f32 v[106:107], v[106:107], v[122:123], v[174:175]
	v_pk_fma_f32 v[108:109], v[108:109], v[124:125], v[176:177]
	v_pk_fma_f32 v[110:111], v[110:111], v[126:127], v[178:179]
	global_load_dwordx4 v[172:175], v[188:189], off offset:16
	global_load_dwordx4 v[176:179], v[188:189], off offset:0
	s_waitcnt vmcnt(8)
	v_pk_fma_f32 v[96:97], v[96:97], v[120:121], v[180:181]
	v_pk_fma_f32 v[98:99], v[98:99], v[122:123], v[182:183]
	v_pk_fma_f32 v[100:101], v[100:101], v[124:125], v[184:185]
	v_pk_fma_f32 v[102:103], v[102:103], v[126:127], v[186:187]
	global_load_dwordx4 v[180:183], v[144:145], off offset:528
	global_load_dwordx4 v[184:187], v[144:145], off offset:512
	s_waitcnt vmcnt(8)
	v_pk_fma_f32 v[88:89], v[88:89], v[120:121], v[204:205]
	v_pk_fma_f32 v[90:91], v[90:91], v[122:123], v[206:207]
	v_pk_fma_f32 v[92:93], v[92:93], v[124:125], v[208:209]
	v_pk_fma_f32 v[94:95], v[94:95], v[126:127], v[210:211]
	global_load_dwordx4 v[204:207], v[244:245], off offset:528
	global_load_dwordx4 v[208:211], v[244:245], off offset:512
	s_waitcnt vmcnt(8)
	v_pk_fma_f32 v[80:81], v[80:81], v[120:121], v[154:155]
	v_pk_fma_f32 v[82:83], v[82:83], v[122:123], v[156:157]
	v_pk_fma_f32 v[84:85], v[84:85], v[124:125], v[158:159]
	v_pk_fma_f32 v[86:87], v[86:87], v[126:127], v[160:161]
	global_load_dwordx4 v[154:157], v[246:247], off offset:528
	global_load_dwordx4 v[158:161], v[246:247], off offset:512
	s_waitcnt vmcnt(8)
	v_pk_fma_f32 v[72:73], v[72:73], v[120:121], v[164:165]
	v_pk_fma_f32 v[74:75], v[74:75], v[122:123], v[166:167]
	v_pk_fma_f32 v[76:77], v[76:77], v[124:125], v[168:169]
	v_pk_fma_f32 v[78:79], v[78:79], v[126:127], v[170:171]
	global_load_dwordx4 v[164:167], v[248:249], off offset:528
	global_load_dwordx4 v[168:171], v[248:249], off offset:512
	s_waitcnt vmcnt(8)
	v_pk_fma_f32 v[60:61], v[60:61], v[120:121], v[172:173]
	v_pk_fma_f32 v[62:63], v[62:63], v[122:123], v[174:175]
	v_pk_fma_f32 v[68:69], v[68:69], v[124:125], v[176:177]
	v_pk_fma_f32 v[70:71], v[70:71], v[126:127], v[178:179]
	global_load_dwordx4 v[172:175], v[250:251], off offset:528
	global_load_dwordx4 v[176:179], v[250:251], off offset:512
	s_waitcnt vmcnt(8)
	v_pk_fma_f32 v[56:57], v[56:57], v[236:237], v[180:181]
	v_pk_fma_f32 v[58:59], v[58:59], v[238:239], v[182:183]
	v_pk_fma_f32 v[64:65], v[64:65], v[240:241], v[184:185]
	v_pk_fma_f32 v[66:67], v[66:67], v[242:243], v[186:187]
	global_load_dwordx4 v[180:183], v[216:217], off offset:528
	global_load_dwordx4 v[184:187], v[216:217], off offset:512
	s_waitcnt vmcnt(8)
	v_pk_fma_f32 v[48:49], v[48:49], v[236:237], v[204:205]
	v_pk_fma_f32 v[50:51], v[50:51], v[238:239], v[206:207]
	v_pk_fma_f32 v[52:53], v[52:53], v[240:241], v[208:209]
	v_pk_fma_f32 v[54:55], v[54:55], v[242:243], v[210:211]
	global_load_dwordx4 v[204:207], v[192:193], off offset:528
	global_load_dwordx4 v[208:211], v[192:193], off offset:512
	s_waitcnt vmcnt(8)
	v_pk_fma_f32 v[40:41], v[40:41], v[236:237], v[154:155]
	v_pk_fma_f32 v[42:43], v[42:43], v[238:239], v[156:157]
	v_pk_fma_f32 v[44:45], v[44:45], v[240:241], v[158:159]
	v_pk_fma_f32 v[46:47], v[46:47], v[242:243], v[160:161]
	global_load_dwordx4 v[154:157], v[188:189], off offset:528
	global_load_dwordx4 v[158:161], v[188:189], off offset:512
	s_waitcnt vmcnt(8)
	v_pk_fma_f32 v[32:33], v[32:33], v[236:237], v[164:165]
	v_pk_fma_f32 v[34:35], v[34:35], v[238:239], v[166:167]
	v_pk_fma_f32 v[36:37], v[36:37], v[240:241], v[168:169]
	v_pk_fma_f32 v[38:39], v[38:39], v[242:243], v[170:171]
	s_waitcnt vmcnt(6)
	v_pk_fma_f32 v[24:25], v[24:25], v[236:237], v[172:173]
	v_pk_fma_f32 v[26:27], v[26:27], v[238:239], v[174:175]
	v_pk_fma_f32 v[28:29], v[28:29], v[240:241], v[176:177]
	v_pk_fma_f32 v[30:31], v[30:31], v[242:243], v[178:179]
	s_waitcnt vmcnt(4)
	v_pk_fma_f32 v[16:17], v[16:17], v[236:237], v[180:181]
	v_pk_fma_f32 v[18:19], v[18:19], v[238:239], v[182:183]
	v_pk_fma_f32 v[20:21], v[20:21], v[240:241], v[184:185]
	v_pk_fma_f32 v[22:23], v[22:23], v[242:243], v[186:187]
	s_waitcnt vmcnt(2)
	v_pk_fma_f32 v[8:9], v[8:9], v[236:237], v[204:205]
	v_pk_fma_f32 v[10:11], v[10:11], v[238:239], v[206:207]
	v_pk_fma_f32 v[12:13], v[12:13], v[240:241], v[208:209]
	v_pk_fma_f32 v[14:15], v[14:15], v[242:243], v[210:211]
	s_waitcnt vmcnt(0)
	v_pk_fma_f32 v[0:1], v[0:1], v[236:237], v[154:155]
	v_pk_fma_f32 v[2:3], v[2:3], v[238:239], v[156:157]
	v_pk_fma_f32 v[4:5], v[4:5], v[240:241], v[158:159]
	v_pk_fma_f32 v[6:7], v[6:7], v[242:243], v[160:161]
	v_pk_mul_f32 v[184:185], v[128:129], v[128:129]
	v_pk_fma_f32 v[184:185], v[130:131], v[130:131], v[184:185]
	v_pk_fma_f32 v[184:185], v[132:133], v[132:133], v[184:185]
	v_pk_fma_f32 v[184:185], v[134:135], v[134:135], v[184:185]
	v_pk_fma_f32 v[184:185], v[56:57], v[56:57], v[184:185]
	v_pk_fma_f32 v[184:185], v[58:59], v[58:59], v[184:185]
	v_pk_fma_f32 v[184:185], v[64:65], v[64:65], v[184:185]
	v_pk_fma_f32 v[184:185], v[66:67], v[66:67], v[184:185]
	v_add_f32_e32 v154, v184, v185
	v_pk_mul_f32 v[184:185], v[112:113], v[112:113]
	v_pk_fma_f32 v[184:185], v[114:115], v[114:115], v[184:185]
	v_pk_fma_f32 v[184:185], v[116:117], v[116:117], v[184:185]
	v_pk_fma_f32 v[184:185], v[118:119], v[118:119], v[184:185]
	v_pk_fma_f32 v[184:185], v[48:49], v[48:49], v[184:185]
	v_pk_fma_f32 v[184:185], v[50:51], v[50:51], v[184:185]
	v_pk_fma_f32 v[184:185], v[52:53], v[52:53], v[184:185]
	v_pk_fma_f32 v[184:185], v[54:55], v[54:55], v[184:185]
	v_add_f32_e32 v155, v184, v185
	v_pk_mul_f32 v[184:185], v[104:105], v[104:105]
	v_pk_fma_f32 v[184:185], v[106:107], v[106:107], v[184:185]
	v_pk_fma_f32 v[184:185], v[108:109], v[108:109], v[184:185]
	v_pk_fma_f32 v[184:185], v[110:111], v[110:111], v[184:185]
	v_pk_fma_f32 v[184:185], v[40:41], v[40:41], v[184:185]
	v_pk_fma_f32 v[184:185], v[42:43], v[42:43], v[184:185]
	v_pk_fma_f32 v[184:185], v[44:45], v[44:45], v[184:185]
	v_pk_fma_f32 v[184:185], v[46:47], v[46:47], v[184:185]
	v_add_f32_e32 v156, v184, v185
	v_pk_mul_f32 v[184:185], v[96:97], v[96:97]
	v_pk_fma_f32 v[184:185], v[98:99], v[98:99], v[184:185]
	v_pk_fma_f32 v[184:185], v[100:101], v[100:101], v[184:185]
	v_pk_fma_f32 v[184:185], v[102:103], v[102:103], v[184:185]
	v_pk_fma_f32 v[184:185], v[32:33], v[32:33], v[184:185]
	v_pk_fma_f32 v[184:185], v[34:35], v[34:35], v[184:185]
	v_pk_fma_f32 v[184:185], v[36:37], v[36:37], v[184:185]
	v_pk_fma_f32 v[184:185], v[38:39], v[38:39], v[184:185]
	v_add_f32_e32 v157, v184, v185
	v_pk_mul_f32 v[184:185], v[88:89], v[88:89]
	v_pk_fma_f32 v[184:185], v[90:91], v[90:91], v[184:185]
	v_pk_fma_f32 v[184:185], v[92:93], v[92:93], v[184:185]
	v_pk_fma_f32 v[184:185], v[94:95], v[94:95], v[184:185]
	v_pk_fma_f32 v[184:185], v[24:25], v[24:25], v[184:185]
	v_pk_fma_f32 v[184:185], v[26:27], v[26:27], v[184:185]
	v_pk_fma_f32 v[184:185], v[28:29], v[28:29], v[184:185]
	v_pk_fma_f32 v[184:185], v[30:31], v[30:31], v[184:185]
	v_add_f32_e32 v158, v184, v185
	v_pk_mul_f32 v[184:185], v[80:81], v[80:81]
	v_pk_fma_f32 v[184:185], v[82:83], v[82:83], v[184:185]
	v_pk_fma_f32 v[184:185], v[84:85], v[84:85], v[184:185]
	v_pk_fma_f32 v[184:185], v[86:87], v[86:87], v[184:185]
	v_pk_fma_f32 v[184:185], v[16:17], v[16:17], v[184:185]
	v_pk_fma_f32 v[184:185], v[18:19], v[18:19], v[184:185]
	v_pk_fma_f32 v[184:185], v[20:21], v[20:21], v[184:185]
	v_pk_fma_f32 v[184:185], v[22:23], v[22:23], v[184:185]
	v_add_f32_e32 v159, v184, v185
	v_pk_mul_f32 v[184:185], v[72:73], v[72:73]
	v_pk_fma_f32 v[184:185], v[74:75], v[74:75], v[184:185]
	v_pk_fma_f32 v[184:185], v[76:77], v[76:77], v[184:185]
	v_pk_fma_f32 v[184:185], v[78:79], v[78:79], v[184:185]
	v_pk_fma_f32 v[184:185], v[8:9], v[8:9], v[184:185]
	v_pk_fma_f32 v[184:185], v[10:11], v[10:11], v[184:185]
	v_pk_fma_f32 v[184:185], v[12:13], v[12:13], v[184:185]
	v_pk_fma_f32 v[184:185], v[14:15], v[14:15], v[184:185]
	v_add_f32_e32 v160, v184, v185
	v_pk_mul_f32 v[184:185], v[60:61], v[60:61]
	v_pk_fma_f32 v[184:185], v[62:63], v[62:63], v[184:185]
	v_pk_fma_f32 v[184:185], v[68:69], v[68:69], v[184:185]
	v_pk_fma_f32 v[184:185], v[70:71], v[70:71], v[184:185]
	v_pk_fma_f32 v[184:185], v[0:1], v[0:1], v[184:185]
	v_pk_fma_f32 v[184:185], v[2:3], v[2:3], v[184:185]
	v_pk_fma_f32 v[184:185], v[4:5], v[4:5], v[184:185]
	v_pk_fma_f32 v[184:185], v[6:7], v[6:7], v[184:185]
	v_add_f32_e32 v161, v184, v185
	v_lshrrev_b32_e32 v186, 1, v152
	s_movk_i32 s44, 80
	v_mad_u32_u24 v186, v150, s44, v186
	s_waitcnt vmcnt(0) lgkmcnt(0)
	s_barrier
	ds_write_b32 v186, v154 offset:0
	ds_write_b32 v186, v155 offset:1280
	ds_write_b32 v186, v156 offset:2560
	ds_write_b32 v186, v157 offset:3840
	ds_write_b32 v186, v158 offset:10240
	ds_write_b32 v186, v159 offset:11520
	ds_write_b32 v186, v160 offset:12800
	ds_write_b32 v186, v161 offset:14080
	s_waitcnt lgkmcnt(0)
	s_barrier
	s_cmpk_gt_u32 s14, 0xff
	s_cbranch_scc1 .Lfz_nord
	v_mul_u32_u24_e32 v186, 80, v197
	ds_read_b128 v[204:207], v186
	ds_read_b128 v[208:211], v186 offset:16
	ds_read_b128 v[212:215], v186 offset:32
	ds_read_b128 v[188:191], v186 offset:48
	s_lshl_b32 s44, s42, 12
	s_lshl_b32 s45, s43, 2
	s_add_i32 s44, s44, s45
	s_add_u32 s44, s96, s44
	s_addc_u32 s45, s97, 0
	s_add_u32 s44, s44, 0x6000000
	s_addc_u32 s45, s45, 0
	v_lshlrev_b32_e32 v187, 4, v197
	s_waitcnt lgkmcnt(0)
	v_add_f32_e32 v204, v204, v205
	v_add_f32_e32 v206, v206, v207
	v_add_f32_e32 v208, v208, v209
	v_add_f32_e32 v210, v210, v211
	v_add_f32_e32 v212, v212, v213
	v_add_f32_e32 v214, v214, v215
	v_add_f32_e32 v188, v188, v189
	v_add_f32_e32 v190, v190, v191
	v_add_f32_e32 v204, v204, v206
	v_add_f32_e32 v208, v208, v210
	v_add_f32_e32 v212, v212, v214
	v_add_f32_e32 v188, v188, v190
	v_add_f32_e32 v204, v204, v208
	v_add_f32_e32 v212, v212, v188
	v_add_f32_e32 v204, v204, v212
	global_store_dword v187, v204, s[44:45]
.Lfz_nord:
	v_mov_b32_e32 v164, v0
	v_mov_b32_e32 v165, v1
	v_mov_b32_e32 v166, v2
	v_mov_b32_e32 v167, v3
	v_mov_b32_e32 v168, v4
	v_mov_b32_e32 v169, v5
	v_mov_b32_e32 v170, v6
	v_mov_b32_e32 v171, v7
	v_mov_b32_e32 v172, v8
	v_mov_b32_e32 v173, v9
	v_mov_b32_e32 v174, v10
	v_mov_b32_e32 v175, v11
	v_mov_b32_e32 v176, v12
	v_mov_b32_e32 v177, v13
	v_mov_b32_e32 v178, v14
	v_mov_b32_e32 v179, v15
	v_mov_b32_e32 v180, v16
	v_mov_b32_e32 v181, v17
	v_mov_b32_e32 v182, v18
	v_mov_b32_e32 v183, v19
	s_mov_b32 s31, s30
	s_mov_b32 s34, s29
	s_mov_b64 s[10:11], s[6:7]
	s_mov_b64 s[8:9], s[0:1]
	s_and_b64 vcc, exec, s[4:5]
	s_waitcnt vmcnt(0)
	s_branch .LBB0_770
.Lfz_normal:
	global_load_dwordx4 v[120:123], v[142:143], off offset:16
	global_load_dwordx4 v[124:127], v[142:143], off
	v_lshl_add_u64 v[144:145], s[8:9], 0, v[162:163]
	v_lshl_add_u64 v[144:145], v[144:145], 0, v[146:147]
	global_load_dwordx4 v[154:157], v[144:145], off offset:16
	global_load_dwordx4 v[158:161], v[144:145], off
	s_and_b64 vcc, exec, s[4:5]
	s_mov_b32 s31, s30
	s_mov_b32 s34, s29
	s_mov_b64 s[10:11], s[6:7]
	s_waitcnt vmcnt(0)
	v_pk_fma_f32 v[130:131], v[130:131], v[122:123], v[156:157]
	v_pk_fma_f32 v[158:159], v[132:133], v[124:125], v[158:159]
	v_lshl_add_u64 v[132:133], s[94:95], 0, v[162:163]
	v_lshl_add_u64 v[132:133], v[132:133], 0, v[146:147]
	v_pk_fma_f32 v[128:129], v[128:129], v[120:121], v[154:155]
	global_store_dwordx4 v[132:133], v[128:131], off offset:16
	v_pk_fma_f32 v[160:161], v[134:135], v[126:127], v[160:161]
	global_store_dwordx4 v[132:133], v[158:161], off
	v_or_b32_e32 v128, 16, v148
	v_ashrrev_i32_e32 v129, 31, v128
	v_lshlrev_b64 v[130:131], 12, v[128:129]
	v_lshl_add_u64 v[128:129], s[8:9], 0, v[130:131]
	v_lshl_add_u64 v[128:129], v[128:129], 0, v[146:147]
	global_load_dwordx4 v[154:157], v[128:129], off offset:16
	global_load_dwordx4 v[158:161], v[128:129], off
	s_waitcnt vmcnt(0)
	v_pk_fma_f32 v[114:115], v[114:115], v[122:123], v[156:157]
	v_pk_fma_f32 v[158:159], v[116:117], v[124:125], v[158:159]
	v_lshl_add_u64 v[116:117], s[94:95], 0, v[130:131]
	v_lshl_add_u64 v[116:117], v[116:117], 0, v[146:147]
	v_pk_fma_f32 v[112:113], v[112:113], v[120:121], v[154:155]
	global_store_dwordx4 v[116:117], v[112:115], off offset:16
	v_pk_fma_f32 v[160:161], v[118:119], v[126:127], v[160:161]
	global_store_dwordx4 v[116:117], v[158:161], off
	v_or_b32_e32 v112, 32, v148
	v_ashrrev_i32_e32 v113, 31, v112
	v_lshlrev_b64 v[114:115], 12, v[112:113]
	v_lshl_add_u64 v[112:113], s[8:9], 0, v[114:115]
	v_lshl_add_u64 v[112:113], v[112:113], 0, v[146:147]
	global_load_dwordx4 v[154:157], v[112:113], off offset:16
	global_load_dwordx4 v[158:161], v[112:113], off
	s_waitcnt vmcnt(0)
	v_pk_fma_f32 v[106:107], v[106:107], v[122:123], v[156:157]
	v_pk_fma_f32 v[158:159], v[108:109], v[124:125], v[158:159]
	v_lshl_add_u64 v[108:109], s[94:95], 0, v[114:115]
	v_lshl_add_u64 v[108:109], v[108:109], 0, v[146:147]
	v_pk_fma_f32 v[104:105], v[104:105], v[120:121], v[154:155]
	global_store_dwordx4 v[108:109], v[104:107], off offset:16
	v_pk_fma_f32 v[160:161], v[110:111], v[126:127], v[160:161]
	global_store_dwordx4 v[108:109], v[158:161], off
	v_or_b32_e32 v104, 48, v148
	v_ashrrev_i32_e32 v105, 31, v104
	v_lshlrev_b64 v[106:107], 12, v[104:105]
	v_lshl_add_u64 v[104:105], s[8:9], 0, v[106:107]
	v_lshl_add_u64 v[104:105], v[104:105], 0, v[146:147]
	global_load_dwordx4 v[154:157], v[104:105], off offset:16
	global_load_dwordx4 v[158:161], v[104:105], off
	s_waitcnt vmcnt(0)
	v_pk_fma_f32 v[98:99], v[98:99], v[122:123], v[156:157]
	v_pk_fma_f32 v[158:159], v[100:101], v[124:125], v[158:159]
	v_lshl_add_u64 v[100:101], s[94:95], 0, v[106:107]
	v_lshl_add_u64 v[100:101], v[100:101], 0, v[146:147]
	v_pk_fma_f32 v[96:97], v[96:97], v[120:121], v[154:155]
	global_store_dwordx4 v[100:101], v[96:99], off offset:16
	v_pk_fma_f32 v[160:161], v[102:103], v[126:127], v[160:161]
	global_store_dwordx4 v[100:101], v[158:161], off
	v_add_u32_e32 v96, 0x80, v148
	v_ashrrev_i32_e32 v97, 31, v96
	v_lshlrev_b64 v[98:99], 12, v[96:97]
	v_lshl_add_u64 v[96:97], s[8:9], 0, v[98:99]
	v_lshl_add_u64 v[96:97], v[96:97], 0, v[146:147]
	global_load_dwordx4 v[154:157], v[96:97], off offset:16
	global_load_dwordx4 v[158:161], v[96:97], off
	s_waitcnt vmcnt(0)
	v_pk_fma_f32 v[90:91], v[90:91], v[122:123], v[156:157]
	v_pk_fma_f32 v[158:159], v[92:93], v[124:125], v[158:159]
	v_lshl_add_u64 v[92:93], s[94:95], 0, v[98:99]
	v_lshl_add_u64 v[92:93], v[92:93], 0, v[146:147]
	v_pk_fma_f32 v[88:89], v[88:89], v[120:121], v[154:155]
	global_store_dwordx4 v[92:93], v[88:91], off offset:16
	v_pk_fma_f32 v[160:161], v[94:95], v[126:127], v[160:161]
	global_store_dwordx4 v[92:93], v[158:161], off
	v_add_u32_e32 v88, 0x90, v148
	v_ashrrev_i32_e32 v89, 31, v88
	v_lshlrev_b64 v[90:91], 12, v[88:89]
	v_lshl_add_u64 v[88:89], s[8:9], 0, v[90:91]
	v_lshl_add_u64 v[88:89], v[88:89], 0, v[146:147]
	global_load_dwordx4 v[154:157], v[88:89], off offset:16
	global_load_dwordx4 v[158:161], v[88:89], off
	s_waitcnt vmcnt(0)
	v_pk_fma_f32 v[82:83], v[82:83], v[122:123], v[156:157]
	v_pk_fma_f32 v[158:159], v[84:85], v[124:125], v[158:159]
	v_lshl_add_u64 v[84:85], s[94:95], 0, v[90:91]
	v_lshl_add_u64 v[84:85], v[84:85], 0, v[146:147]
	v_pk_fma_f32 v[80:81], v[80:81], v[120:121], v[154:155]
	global_store_dwordx4 v[84:85], v[80:83], off offset:16
	v_pk_fma_f32 v[160:161], v[86:87], v[126:127], v[160:161]
	global_store_dwordx4 v[84:85], v[158:161], off
	v_add_u32_e32 v80, 0xa0, v148
	v_ashrrev_i32_e32 v81, 31, v80
	v_lshlrev_b64 v[82:83], 12, v[80:81]
	v_lshl_add_u64 v[80:81], s[8:9], 0, v[82:83]
	v_lshl_add_u64 v[80:81], v[80:81], 0, v[146:147]
	global_load_dwordx4 v[154:157], v[80:81], off offset:16
	global_load_dwordx4 v[158:161], v[80:81], off
	s_waitcnt vmcnt(0)
	v_pk_fma_f32 v[74:75], v[74:75], v[122:123], v[156:157]
	v_pk_fma_f32 v[158:159], v[76:77], v[124:125], v[158:159]
	v_lshl_add_u64 v[76:77], s[94:95], 0, v[82:83]
	v_lshl_add_u64 v[76:77], v[76:77], 0, v[146:147]
	v_pk_fma_f32 v[72:73], v[72:73], v[120:121], v[154:155]
	global_store_dwordx4 v[76:77], v[72:75], off offset:16
	v_pk_fma_f32 v[160:161], v[78:79], v[126:127], v[160:161]
	global_store_dwordx4 v[76:77], v[158:161], off
	v_add_u32_e32 v72, 0xb0, v148
	v_ashrrev_i32_e32 v73, 31, v72
	v_lshlrev_b64 v[74:75], 12, v[72:73]
	v_lshl_add_u64 v[72:73], s[8:9], 0, v[74:75]
	v_lshl_add_u64 v[72:73], v[72:73], 0, v[146:147]
	global_load_dwordx4 v[154:157], v[72:73], off offset:16
	global_load_dwordx4 v[158:161], v[72:73], off
	v_lshl_add_u64 v[74:75], s[94:95], 0, v[74:75]
	v_lshl_add_u64 v[74:75], v[74:75], 0, v[146:147]
	s_mov_b64 s[8:9], s[0:1]
	s_waitcnt vmcnt(0)
	v_pk_fma_f32 v[62:63], v[62:63], v[122:123], v[156:157]
	v_pk_fma_f32 v[70:71], v[70:71], v[126:127], v[160:161]
	v_pk_fma_f32 v[68:69], v[68:69], v[124:125], v[158:159]
	v_pk_fma_f32 v[60:61], v[60:61], v[120:121], v[154:155]
	global_store_dwordx4 v[74:75], v[68:71], off
	global_store_dwordx4 v[74:75], v[60:63], off offset:16
	global_load_dwordx4 v[60:63], v[142:143], off offset:528
	s_nop 0
	global_load_dwordx4 v[68:71], v[142:143], off offset:512
	global_load_dwordx4 v[118:121], v[144:145], off offset:528
	global_load_dwordx4 v[122:125], v[144:145], off offset:512
	s_waitcnt vmcnt(0)
	v_pk_fma_f32 v[58:59], v[58:59], v[62:63], v[120:121]
	v_pk_fma_f32 v[66:67], v[66:67], v[70:71], v[124:125]
	v_pk_fma_f32 v[64:65], v[64:65], v[68:69], v[122:123]
	v_pk_fma_f32 v[56:57], v[56:57], v[60:61], v[118:119]
	global_store_dwordx4 v[132:133], v[64:67], off offset:512
	global_store_dwordx4 v[132:133], v[56:59], off offset:528
	global_load_dwordx4 v[56:59], v[128:129], off offset:528
	s_nop 0
	global_load_dwordx4 v[64:67], v[128:129], off offset:512
	s_waitcnt vmcnt(0)
	v_pk_fma_f32 v[50:51], v[50:51], v[62:63], v[58:59]
	v_pk_fma_f32 v[54:55], v[54:55], v[70:71], v[66:67]
	v_pk_fma_f32 v[52:53], v[52:53], v[68:69], v[64:65]
	v_pk_fma_f32 v[48:49], v[48:49], v[60:61], v[56:57]
	global_store_dwordx4 v[116:117], v[52:55], off offset:512
	global_store_dwordx4 v[116:117], v[48:51], off offset:528
	global_load_dwordx4 v[48:51], v[112:113], off offset:528
	s_nop 0
	global_load_dwordx4 v[52:55], v[112:113], off offset:512
	s_waitcnt vmcnt(0)
	v_pk_fma_f32 v[42:43], v[42:43], v[62:63], v[50:51]
	v_pk_fma_f32 v[46:47], v[46:47], v[70:71], v[54:55]
	v_pk_fma_f32 v[44:45], v[44:45], v[68:69], v[52:53]
	v_pk_fma_f32 v[40:41], v[40:41], v[60:61], v[48:49]
	global_store_dwordx4 v[108:109], v[44:47], off offset:512
	global_store_dwordx4 v[108:109], v[40:43], off offset:528
	global_load_dwordx4 v[40:43], v[104:105], off offset:528
	s_nop 0
	global_load_dwordx4 v[44:47], v[104:105], off offset:512
	s_waitcnt vmcnt(0)
	v_pk_fma_f32 v[34:35], v[34:35], v[62:63], v[42:43]
	v_pk_fma_f32 v[38:39], v[38:39], v[70:71], v[46:47]
	v_pk_fma_f32 v[36:37], v[36:37], v[68:69], v[44:45]
	v_pk_fma_f32 v[32:33], v[32:33], v[60:61], v[40:41]
	global_store_dwordx4 v[100:101], v[36:39], off offset:512
	global_store_dwordx4 v[100:101], v[32:35], off offset:528
	global_load_dwordx4 v[32:35], v[96:97], off offset:528
	s_nop 0
	global_load_dwordx4 v[36:39], v[96:97], off offset:512
	s_waitcnt vmcnt(0)
	v_pk_fma_f32 v[26:27], v[26:27], v[62:63], v[34:35]
	v_pk_fma_f32 v[30:31], v[30:31], v[70:71], v[38:39]
	v_pk_fma_f32 v[28:29], v[28:29], v[68:69], v[36:37]
	v_pk_fma_f32 v[24:25], v[24:25], v[60:61], v[32:33]
	global_store_dwordx4 v[92:93], v[28:31], off offset:512
	global_store_dwordx4 v[92:93], v[24:27], off offset:528
	global_load_dwordx4 v[24:27], v[88:89], off offset:528
	s_nop 0
	global_load_dwordx4 v[28:31], v[88:89], off offset:512
	s_waitcnt vmcnt(0)
	v_pk_fma_f32 v[18:19], v[18:19], v[62:63], v[26:27]
	v_pk_fma_f32 v[22:23], v[22:23], v[70:71], v[30:31]
	v_pk_fma_f32 v[20:21], v[20:21], v[68:69], v[28:29]
	v_pk_fma_f32 v[16:17], v[16:17], v[60:61], v[24:25]
	global_store_dwordx4 v[84:85], v[20:23], off offset:512
	global_store_dwordx4 v[84:85], v[16:19], off offset:528
	global_load_dwordx4 v[16:19], v[80:81], off offset:528
	s_nop 0
	global_load_dwordx4 v[20:23], v[80:81], off offset:512
	s_waitcnt vmcnt(0)
	v_pk_fma_f32 v[10:11], v[10:11], v[62:63], v[18:19]
	v_pk_fma_f32 v[14:15], v[14:15], v[70:71], v[22:23]
	v_pk_fma_f32 v[12:13], v[12:13], v[68:69], v[20:21]
	v_pk_fma_f32 v[8:9], v[8:9], v[60:61], v[16:17]
	global_store_dwordx4 v[76:77], v[12:15], off offset:512
	global_store_dwordx4 v[76:77], v[8:11], off offset:528
	global_load_dwordx4 v[8:11], v[72:73], off offset:528
	s_nop 0
	global_load_dwordx4 v[12:15], v[72:73], off offset:512
	s_waitcnt vmcnt(0)
	v_pk_fma_f32 v[2:3], v[2:3], v[62:63], v[10:11]
	v_pk_fma_f32 v[6:7], v[6:7], v[70:71], v[14:15]
	v_pk_fma_f32 v[4:5], v[4:5], v[68:69], v[12:13]
	v_pk_fma_f32 v[0:1], v[0:1], v[60:61], v[8:9]
	global_store_dwordx4 v[74:75], v[4:7], off offset:512
	global_store_dwordx4 v[74:75], v[0:3], off offset:528
.Lfz_done:
	s_cbranch_vccz .LBB0_763
	s_waitcnt vmcnt(0)
	s_cmpk_gt_u32 s14, 0xff
	s_cbranch_scc1 .LBB0_770
	s_barrier

.LBB0_859:
	s_add_u32 s44, s96, 0x6000000
	s_addc_u32 s45, s97, 0
	v_lshlrev_b32_e32 v158, 4, v148
	global_load_dwordx4 v[0:3], v158, s[44:45] offset:0
	global_load_dwordx4 v[4:7], v158, s[44:45] offset:256
	global_load_dwordx4 v[8:11], v158, s[44:45] offset:512
	global_load_dwordx4 v[12:15], v158, s[44:45] offset:768
	global_load_dwordx4 v[16:19], v158, s[44:45] offset:2048
	global_load_dwordx4 v[120:123], v158, s[44:45] offset:2304
	global_load_dwordx4 v[124:127], v158, s[44:45] offset:2560
	global_load_dwordx4 v[154:157], v158, s[44:45] offset:2816
	v_lshl_add_u64 v[160:161], s[92:93], 0, v[146:147]
	global_load_dwordx4 v[236:239], v[160:161], off offset:16
	global_load_dwordx4 v[240:243], v[160:161], off
	global_load_dwordx4 v[204:207], v[160:161], off offset:528
	global_load_dwordx4 v[208:211], v[160:161], off offset:512
	v_lshlrev_b32_e32 v162, 12, v148
	v_mov_b32_e32 v163, 0
	v_lshl_add_u64 v[162:163], s[94:95], 0, v[162:163]
	v_lshl_add_u64 v[162:163], v[162:163], 0, v[146:147]
	v_mov_b32_e32 v159, 0x358637bd
	s_mov_b32 s42, 0x800000
	s_waitcnt vmcnt(0)
	v_add_f32_e32 v0, v0, v1
	v_add_f32_e32 v0, v0, v2
	v_add_f32_e32 v0, v0, v3
	v_fmamk_f32 v0, v0, 0x3a800000, v159
	v_mul_f32_e32 v1, 0x4b800000, v0
	v_cmp_gt_f32_e32 vcc, s42, v0
	s_nop 1
	v_cndmask_b32_e32 v0, v0, v1, vcc
	v_rsq_f32_e32 v0, v0
	s_nop 0
	v_mul_f32_e32 v1, 0x45800000, v0
	v_cndmask_b32_e32 v2, v0, v1, vcc
	v_pk_mul_f32 v[128:129], v[128:129], v[2:3] op_sel_hi:[1,0]
	v_pk_mul_f32 v[130:131], v[130:131], v[2:3] op_sel_hi:[1,0]
	v_pk_mul_f32 v[128:129], v[236:237], v[128:129]
	v_pk_mul_f32 v[130:131], v[238:239], v[130:131]
	global_store_dwordx4 v[162:163], v[128:131], off offset:16
	v_pk_mul_f32 v[132:133], v[132:133], v[2:3] op_sel_hi:[1,0]
	v_pk_mul_f32 v[134:135], v[134:135], v[2:3] op_sel_hi:[1,0]
	v_pk_mul_f32 v[132:133], v[240:241], v[132:133]
	v_pk_mul_f32 v[134:135], v[242:243], v[134:135]
	global_store_dwordx4 v[162:163], v[132:135], off offset:0
	v_pk_mul_f32 v[56:57], v[56:57], v[2:3] op_sel_hi:[1,0]
	v_pk_mul_f32 v[58:59], v[58:59], v[2:3] op_sel_hi:[1,0]
	v_pk_mul_f32 v[56:57], v[204:205], v[56:57]
	v_pk_mul_f32 v[58:59], v[206:207], v[58:59]
	global_store_dwordx4 v[162:163], v[56:59], off offset:528
	v_pk_mul_f32 v[64:65], v[64:65], v[2:3] op_sel_hi:[1,0]
	v_pk_mul_f32 v[66:67], v[66:67], v[2:3] op_sel_hi:[1,0]
	v_pk_mul_f32 v[64:65], v[208:209], v[64:65]
	v_pk_mul_f32 v[66:67], v[210:211], v[66:67]
	global_store_dwordx4 v[162:163], v[64:67], off offset:512
	v_add_f32_e32 v4, v4, v5
	v_add_f32_e32 v4, v4, v6
	v_add_f32_e32 v4, v4, v7
	v_fmamk_f32 v4, v4, 0x3a800000, v159
	v_mul_f32_e32 v5, 0x4b800000, v4
	v_cmp_gt_f32_e32 vcc, s42, v4
	s_nop 1
	v_cndmask_b32_e32 v4, v4, v5, vcc
	v_rsq_f32_e32 v4, v4
	s_nop 0
	v_mul_f32_e32 v5, 0x45800000, v4
	v_cndmask_b32_e32 v6, v4, v5, vcc
	s_mov_b64 s[44:45], 0x10000
	v_lshl_add_u64 v[212:213], v[162:163], 0, s[44:45]
	v_pk_mul_f32 v[112:113], v[112:113], v[6:7] op_sel_hi:[1,0]
	v_pk_mul_f32 v[114:115], v[114:115], v[6:7] op_sel_hi:[1,0]
	v_pk_mul_f32 v[112:113], v[236:237], v[112:113]
	v_pk_mul_f32 v[114:115], v[238:239], v[114:115]
	global_store_dwordx4 v[212:213], v[112:115], off offset:16
	v_pk_mul_f32 v[116:117], v[116:117], v[6:7] op_sel_hi:[1,0]
	v_pk_mul_f32 v[118:119], v[118:119], v[6:7] op_sel_hi:[1,0]
	v_pk_mul_f32 v[116:117], v[240:241], v[116:117]
	v_pk_mul_f32 v[118:119], v[242:243], v[118:119]
	global_store_dwordx4 v[212:213], v[116:119], off offset:0
	v_pk_mul_f32 v[48:49], v[48:49], v[6:7] op_sel_hi:[1,0]
	v_pk_mul_f32 v[50:51], v[50:51], v[6:7] op_sel_hi:[1,0]
	v_pk_mul_f32 v[48:49], v[204:205], v[48:49]
	v_pk_mul_f32 v[50:51], v[206:207], v[50:51]
	global_store_dwordx4 v[212:213], v[48:51], off offset:528
	v_pk_mul_f32 v[52:53], v[52:53], v[6:7] op_sel_hi:[1,0]
	v_pk_mul_f32 v[54:55], v[54:55], v[6:7] op_sel_hi:[1,0]
	v_pk_mul_f32 v[52:53], v[208:209], v[52:53]
	v_pk_mul_f32 v[54:55], v[210:211], v[54:55]
	global_store_dwordx4 v[212:213], v[52:55], off offset:512
	v_add_f32_e32 v8, v8, v9
	v_add_f32_e32 v8, v8, v10
	v_add_f32_e32 v8, v8, v11
	v_fmamk_f32 v8, v8, 0x3a800000, v159
	v_mul_f32_e32 v9, 0x4b800000, v8
	v_cmp_gt_f32_e32 vcc, s42, v8
	s_nop 1
	v_cndmask_b32_e32 v8, v8, v9, vcc
	v_rsq_f32_e32 v8, v8
	s_nop 0
	v_mul_f32_e32 v9, 0x45800000, v8
	v_cndmask_b32_e32 v10, v8, v9, vcc
	s_mov_b64 s[44:45], 0x20000
	v_lshl_add_u64 v[214:215], v[162:163], 0, s[44:45]
	v_pk_mul_f32 v[104:105], v[104:105], v[10:11] op_sel_hi:[1,0]
	v_pk_mul_f32 v[106:107], v[106:107], v[10:11] op_sel_hi:[1,0]
	v_pk_mul_f32 v[104:105], v[236:237], v[104:105]
	v_pk_mul_f32 v[106:107], v[238:239], v[106:107]
	global_store_dwordx4 v[214:215], v[104:107], off offset:16
	v_pk_mul_f32 v[108:109], v[108:109], v[10:11] op_sel_hi:[1,0]
	v_pk_mul_f32 v[110:111], v[110:111], v[10:11] op_sel_hi:[1,0]
	v_pk_mul_f32 v[108:109], v[240:241], v[108:109]
	v_pk_mul_f32 v[110:111], v[242:243], v[110:111]
	global_store_dwordx4 v[214:215], v[108:111], off offset:0
	v_pk_mul_f32 v[40:41], v[40:41], v[10:11] op_sel_hi:[1,0]
	v_pk_mul_f32 v[42:43], v[42:43], v[10:11] op_sel_hi:[1,0]
	v_pk_mul_f32 v[40:41], v[204:205], v[40:41]
	v_pk_mul_f32 v[42:43], v[206:207], v[42:43]
	global_store_dwordx4 v[214:215], v[40:43], off offset:528
	v_pk_mul_f32 v[44:45], v[44:45], v[10:11] op_sel_hi:[1,0]
	v_pk_mul_f32 v[46:47], v[46:47], v[10:11] op_sel_hi:[1,0]
	v_pk_mul_f32 v[44:45], v[208:209], v[44:45]
	v_pk_mul_f32 v[46:47], v[210:211], v[46:47]
	global_store_dwordx4 v[214:215], v[44:47], off offset:512
	v_add_f32_e32 v12, v12, v13
	v_add_f32_e32 v12, v12, v14
	v_add_f32_e32 v12, v12, v15
	v_fmamk_f32 v12, v12, 0x3a800000, v159
	v_mul_f32_e32 v13, 0x4b800000, v12
	v_cmp_gt_f32_e32 vcc, s42, v12
	s_nop 1
	v_cndmask_b32_e32 v12, v12, v13, vcc
	v_rsq_f32_e32 v12, v12
	s_nop 0
	v_mul_f32_e32 v13, 0x45800000, v12
	v_cndmask_b32_e32 v14, v12, v13, vcc
	s_mov_b64 s[44:45], 0x30000
	v_lshl_add_u64 v[212:213], v[162:163], 0, s[44:45]
	v_pk_mul_f32 v[96:97], v[96:97], v[14:15] op_sel_hi:[1,0]
	v_pk_mul_f32 v[98:99], v[98:99], v[14:15] op_sel_hi:[1,0]
	v_pk_mul_f32 v[96:97], v[236:237], v[96:97]
	v_pk_mul_f32 v[98:99], v[238:239], v[98:99]
	global_store_dwordx4 v[212:213], v[96:99], off offset:16
	v_pk_mul_f32 v[100:101], v[100:101], v[14:15] op_sel_hi:[1,0]
	v_pk_mul_f32 v[102:103], v[102:103], v[14:15] op_sel_hi:[1,0]
	v_pk_mul_f32 v[100:101], v[240:241], v[100:101]
	v_pk_mul_f32 v[102:103], v[242:243], v[102:103]
	global_store_dwordx4 v[212:213], v[100:103], off offset:0
	v_pk_mul_f32 v[32:33], v[32:33], v[14:15] op_sel_hi:[1,0]
	v_pk_mul_f32 v[34:35], v[34:35], v[14:15] op_sel_hi:[1,0]
	v_pk_mul_f32 v[32:33], v[204:205], v[32:33]
	v_pk_mul_f32 v[34:35], v[206:207], v[34:35]
	global_store_dwordx4 v[212:213], v[32:35], off offset:528
	v_pk_mul_f32 v[36:37], v[36:37], v[14:15] op_sel_hi:[1,0]
	v_pk_mul_f32 v[38:39], v[38:39], v[14:15] op_sel_hi:[1,0]
	v_pk_mul_f32 v[36:37], v[208:209], v[36:37]
	v_pk_mul_f32 v[38:39], v[210:211], v[38:39]
	global_store_dwordx4 v[212:213], v[36:39], off offset:512
	v_add_f32_e32 v16, v16, v17
	v_add_f32_e32 v16, v16, v18
	v_add_f32_e32 v16, v16, v19
	v_fmamk_f32 v16, v16, 0x3a800000, v159
	v_mul_f32_e32 v17, 0x4b800000, v16
	v_cmp_gt_f32_e32 vcc, s42, v16
	s_nop 1
	v_cndmask_b32_e32 v16, v16, v17, vcc
	v_rsq_f32_e32 v16, v16
	s_nop 0
	v_mul_f32_e32 v17, 0x45800000, v16
	v_cndmask_b32_e32 v18, v16, v17, vcc
	s_mov_b64 s[44:45], 0x80000
	v_lshl_add_u64 v[214:215], v[162:163], 0, s[44:45]
	v_pk_mul_f32 v[88:89], v[88:89], v[18:19] op_sel_hi:[1,0]
	v_pk_mul_f32 v[90:91], v[90:91], v[18:19] op_sel_hi:[1,0]
	v_pk_mul_f32 v[88:89], v[236:237], v[88:89]
	v_pk_mul_f32 v[90:91], v[238:239], v[90:91]
	global_store_dwordx4 v[214:215], v[88:91], off offset:16
	v_pk_mul_f32 v[92:93], v[92:93], v[18:19] op_sel_hi:[1,0]
	v_pk_mul_f32 v[94:95], v[94:95], v[18:19] op_sel_hi:[1,0]
	v_pk_mul_f32 v[92:93], v[240:241], v[92:93]
	v_pk_mul_f32 v[94:95], v[242:243], v[94:95]
	global_store_dwordx4 v[214:215], v[92:95], off offset:0
	v_pk_mul_f32 v[24:25], v[24:25], v[18:19] op_sel_hi:[1,0]
	v_pk_mul_f32 v[26:27], v[26:27], v[18:19] op_sel_hi:[1,0]
	v_pk_mul_f32 v[24:25], v[204:205], v[24:25]
	v_pk_mul_f32 v[26:27], v[206:207], v[26:27]
	global_store_dwordx4 v[214:215], v[24:27], off offset:528
	v_pk_mul_f32 v[28:29], v[28:29], v[18:19] op_sel_hi:[1,0]
	v_pk_mul_f32 v[30:31], v[30:31], v[18:19] op_sel_hi:[1,0]
	v_pk_mul_f32 v[28:29], v[208:209], v[28:29]
	v_pk_mul_f32 v[30:31], v[210:211], v[30:31]
	global_store_dwordx4 v[214:215], v[28:31], off offset:512
	v_add_f32_e32 v120, v120, v121
	v_add_f32_e32 v120, v120, v122
	v_add_f32_e32 v120, v120, v123
	v_fmamk_f32 v120, v120, 0x3a800000, v159
	v_mul_f32_e32 v121, 0x4b800000, v120
	v_cmp_gt_f32_e32 vcc, s42, v120
	s_nop 1
	v_cndmask_b32_e32 v120, v120, v121, vcc
	v_rsq_f32_e32 v120, v120
	s_nop 0
	v_mul_f32_e32 v121, 0x45800000, v120
	v_cndmask_b32_e32 v122, v120, v121, vcc
	s_mov_b64 s[44:45], 0x90000
	v_lshl_add_u64 v[212:213], v[162:163], 0, s[44:45]
	v_pk_mul_f32 v[80:81], v[80:81], v[122:123] op_sel_hi:[1,0]
	v_pk_mul_f32 v[82:83], v[82:83], v[122:123] op_sel_hi:[1,0]
	v_pk_mul_f32 v[80:81], v[236:237], v[80:81]
	v_pk_mul_f32 v[82:83], v[238:239], v[82:83]
	global_store_dwordx4 v[212:213], v[80:83], off offset:16
	v_pk_mul_f32 v[84:85], v[84:85], v[122:123] op_sel_hi:[1,0]
	v_pk_mul_f32 v[86:87], v[86:87], v[122:123] op_sel_hi:[1,0]
	v_pk_mul_f32 v[84:85], v[240:241], v[84:85]
	v_pk_mul_f32 v[86:87], v[242:243], v[86:87]
	global_store_dwordx4 v[212:213], v[84:87], off offset:0
	v_pk_mul_f32 v[180:181], v[180:181], v[122:123] op_sel_hi:[1,0]
	v_pk_mul_f32 v[182:183], v[182:183], v[122:123] op_sel_hi:[1,0]
	v_pk_mul_f32 v[180:181], v[204:205], v[180:181]
	v_pk_mul_f32 v[182:183], v[206:207], v[182:183]
	global_store_dwordx4 v[212:213], v[180:183], off offset:528
	v_pk_mul_f32 v[20:21], v[20:21], v[122:123] op_sel_hi:[1,0]
	v_pk_mul_f32 v[22:23], v[22:23], v[122:123] op_sel_hi:[1,0]
	v_pk_mul_f32 v[20:21], v[208:209], v[20:21]
	v_pk_mul_f32 v[22:23], v[210:211], v[22:23]
	global_store_dwordx4 v[212:213], v[20:23], off offset:512
	v_add_f32_e32 v124, v124, v125
	v_add_f32_e32 v124, v124, v126
	v_add_f32_e32 v124, v124, v127
	v_fmamk_f32 v124, v124, 0x3a800000, v159
	v_mul_f32_e32 v125, 0x4b800000, v124
	v_cmp_gt_f32_e32 vcc, s42, v124
	s_nop 1
	v_cndmask_b32_e32 v124, v124, v125, vcc
	v_rsq_f32_e32 v124, v124
	s_nop 0
	v_mul_f32_e32 v125, 0x45800000, v124
	v_cndmask_b32_e32 v126, v124, v125, vcc
	s_mov_b64 s[44:45], 0xa0000
	v_lshl_add_u64 v[214:215], v[162:163], 0, s[44:45]
	v_pk_mul_f32 v[72:73], v[72:73], v[126:127] op_sel_hi:[1,0]
	v_pk_mul_f32 v[74:75], v[74:75], v[126:127] op_sel_hi:[1,0]
	v_pk_mul_f32 v[72:73], v[236:237], v[72:73]
	v_pk_mul_f32 v[74:75], v[238:239], v[74:75]
	global_store_dwordx4 v[214:215], v[72:75], off offset:16
	v_pk_mul_f32 v[76:77], v[76:77], v[126:127] op_sel_hi:[1,0]
	v_pk_mul_f32 v[78:79], v[78:79], v[126:127] op_sel_hi:[1,0]
	v_pk_mul_f32 v[76:77], v[240:241], v[76:77]
	v_pk_mul_f32 v[78:79], v[242:243], v[78:79]
	global_store_dwordx4 v[214:215], v[76:79], off offset:0
	v_pk_mul_f32 v[172:173], v[172:173], v[126:127] op_sel_hi:[1,0]
	v_pk_mul_f32 v[174:175], v[174:175], v[126:127] op_sel_hi:[1,0]
	v_pk_mul_f32 v[172:173], v[204:205], v[172:173]
	v_pk_mul_f32 v[174:175], v[206:207], v[174:175]
	global_store_dwordx4 v[214:215], v[172:175], off offset:528
	v_pk_mul_f32 v[176:177], v[176:177], v[126:127] op_sel_hi:[1,0]
	v_pk_mul_f32 v[178:179], v[178:179], v[126:127] op_sel_hi:[1,0]
	v_pk_mul_f32 v[176:177], v[208:209], v[176:177]
	v_pk_mul_f32 v[178:179], v[210:211], v[178:179]
	global_store_dwordx4 v[214:215], v[176:179], off offset:512
	v_add_f32_e32 v154, v154, v155
	v_add_f32_e32 v154, v154, v156
	v_add_f32_e32 v154, v154, v157
	v_fmamk_f32 v154, v154, 0x3a800000, v159
	v_mul_f32_e32 v155, 0x4b800000, v154
	v_cmp_gt_f32_e32 vcc, s42, v154
	s_nop 1
	v_cndmask_b32_e32 v154, v154, v155, vcc
	v_rsq_f32_e32 v154, v154
	s_nop 0
	v_mul_f32_e32 v155, 0x45800000, v154
	v_cndmask_b32_e32 v156, v154, v155, vcc
	s_mov_b64 s[44:45], 0xb0000
	v_lshl_add_u64 v[212:213], v[162:163], 0, s[44:45]
	v_pk_mul_f32 v[60:61], v[60:61], v[156:157] op_sel_hi:[1,0]
	v_pk_mul_f32 v[62:63], v[62:63], v[156:157] op_sel_hi:[1,0]
	v_pk_mul_f32 v[60:61], v[236:237], v[60:61]
	v_pk_mul_f32 v[62:63], v[238:239], v[62:63]
	global_store_dwordx4 v[212:213], v[60:63], off offset:16
	v_pk_mul_f32 v[68:69], v[68:69], v[156:157] op_sel_hi:[1,0]
	v_pk_mul_f32 v[70:71], v[70:71], v[156:157] op_sel_hi:[1,0]
	v_pk_mul_f32 v[68:69], v[240:241], v[68:69]
	v_pk_mul_f32 v[70:71], v[242:243], v[70:71]
	global_store_dwordx4 v[212:213], v[68:71], off offset:0
	v_pk_mul_f32 v[164:165], v[164:165], v[156:157] op_sel_hi:[1,0]
	v_pk_mul_f32 v[166:167], v[166:167], v[156:157] op_sel_hi:[1,0]
	v_pk_mul_f32 v[164:165], v[204:205], v[164:165]
	v_pk_mul_f32 v[166:167], v[206:207], v[166:167]
	global_store_dwordx4 v[212:213], v[164:167], off offset:528
	v_pk_mul_f32 v[168:169], v[168:169], v[156:157] op_sel_hi:[1,0]
	v_pk_mul_f32 v[170:171], v[170:171], v[156:157] op_sel_hi:[1,0]
	v_pk_mul_f32 v[168:169], v[208:209], v[168:169]
	v_pk_mul_f32 v[170:171], v[210:211], v[170:171]
	global_store_dwordx4 v[212:213], v[168:171], off offset:512
	s_endpgm
